# grid barrier: every workgroup writes back the XCD L2 (buffer_wbl2) before its own arrival, the last arriver's full flush removed; on top of v68
# baseline (speedup 1.0000x reference)
; __device__ __forceinline__ unsigned xb_add(unsigned* p, unsigned v) { return __hip_atomic_fetch_add(p, v, __ATOMIC_RELAXED, __HIP_MEMORY_SCOPE_AGENT); }
; __device__ __forceinline__ void xcd_barrier(const XcdBarrier& b) {
;     asm volatile("s_waitcnt vmcnt(0)" ::: "memory");
;     __syncthreads();
;     if (threadIdx.x == 0) {
;         unsigned* bar = b.bar;
;         __builtin_amdgcn_s_waitcnt(0);
;         unsigned nloc = b.st[0], nx = b.st[1];
;         if (nloc == 0u) { xcd_barrier_complete(bar, b.x, nloc, nx); b.st[0] = nloc; b.st[1] = nx; }
;         const unsigned old = xb_add(&bar[XB_XSUB(b.x)], 1u);
;         const unsigned gen = old / nloc;
;         if (old + 1u == (gen + 1u) * nloc) {
;             __builtin_amdgcn_fence(__ATOMIC_RELEASE, "agent");
;             asm volatile("s_waitcnt vmcnt(0)" ::: "memory");
;             const unsigned og = xb_add(&bar[XB_TOP], 1u);
.LBB0_88:
	s_mov_b64 s[8:9], exec
	s_lshl_b32 s3, s2, 8
	v_mbcnt_lo_u32_b32 v2, s8, 0
	s_add_u32 s6, s0, s3
	v_mbcnt_hi_u32_b32 v2, s9, v2
	s_addc_u32 s7, s1, 0
	v_cmp_eq_u32_e32 vcc, 0, v2
	s_and_saveexec_b64 s[10:11], vcc
	s_cbranch_execz .LBB0_90
	s_bcnt1_i32_b64 s3, s[8:9]
	v_mov_b32_e32 v4, 0x1000
	v_mov_b32_e32 v5, s3
	buffer_wbl2 sc1
	s_waitcnt vmcnt(0)
	global_atomic_add v4, v4, v5, s[6:7] offset:1024 sc0

; __device__ __forceinline__ unsigned xb_add(unsigned* p, unsigned v) { return __hip_atomic_fetch_add(p, v, __ATOMIC_RELAXED, __HIP_MEMORY_SCOPE_AGENT); }
; __device__ __forceinline__ void xcd_barrier(const XcdBarrier& b) {
;     ...
;         if (old + 1u == (gen + 1u) * nloc) {
;             __builtin_amdgcn_fence(__ATOMIC_RELEASE, "agent");
;             asm volatile("s_waitcnt vmcnt(0)" ::: "memory");
;             const unsigned og = xb_add(&bar[XB_TOP], 1u);
;             const unsigned tg = og / nx;
;             if (og + 1u == (tg + 1u) * nx) xb_add(&bar[XB_TOPGEN], 1u);
.LBB0_104:
	s_andn2_saveexec_b64 s[8:9], s[8:9]
	s_cbranch_execz .LBB0_124
	s_mov_b64 s[10:11], exec
	s_waitcnt lgkmcnt(0)
	s_waitcnt vmcnt(0)
	v_mbcnt_lo_u32_b32 v2, s10, 0
	v_mbcnt_hi_u32_b32 v2, s11, v2
	v_cmp_eq_u32_e32 vcc, 0, v2
	s_and_saveexec_b64 s[12:13], vcc
	s_cbranch_execz .LBB0_107
	s_bcnt1_i32_b64 s3, s[10:11]
	v_mov_b32_e32 v3, 0x7000
	v_mov_b32_e32 v4, s3
	global_atomic_add v3, v3, v4, s[88:89] offset:1024 sc0

; __device__ __forceinline__ unsigned xb_add(unsigned* p, unsigned v) { return __hip_atomic_fetch_add(p, v, __ATOMIC_RELAXED, __HIP_MEMORY_SCOPE_AGENT); }
; __device__ __forceinline__ void xcd_barrier(const XcdBarrier& b) {
;     asm volatile("s_waitcnt vmcnt(0)" ::: "memory");
;     __syncthreads();
;     if (threadIdx.x == 0) {
;         unsigned* bar = b.bar;
;         __builtin_amdgcn_s_waitcnt(0);
;         unsigned nloc = b.st[0], nx = b.st[1];
;         if (nloc == 0u) { xcd_barrier_complete(bar, b.x, nloc, nx); b.st[0] = nloc; b.st[1] = nx; }
;         const unsigned old = xb_add(&bar[XB_XSUB(b.x)], 1u);
.LBB0_171:
	s_mov_b64 s[38:39], exec
	v_mbcnt_lo_u32_b32 v3, s38, 0
	v_mbcnt_hi_u32_b32 v3, s39, v3
	v_cmp_eq_u32_e32 vcc, 0, v3
	s_and_saveexec_b64 s[34:35], vcc
	s_cbranch_execz .LBB0_173
	s_bcnt1_i32_b64 s1, s[38:39]
	v_readlane_b32 s2, v252, 63
	v_mov_b32_e32 v5, s1
	v_readlane_b32 s3, v253, 0
	s_nop 4
	buffer_wbl2 sc1
	s_waitcnt vmcnt(0)
	global_atomic_add v5, v175, v5, s[2:3] sc0

; __device__ __forceinline__ unsigned xb_add(unsigned* p, unsigned v) { return __hip_atomic_fetch_add(p, v, __ATOMIC_RELAXED, __HIP_MEMORY_SCOPE_AGENT); }
; __device__ __forceinline__ void xcd_barrier(const XcdBarrier& b) {
;     ...
;         if (old + 1u == (gen + 1u) * nloc) {
;             __builtin_amdgcn_fence(__ATOMIC_RELEASE, "agent");
;             asm volatile("s_waitcnt vmcnt(0)" ::: "memory");
;             const unsigned og = xb_add(&bar[XB_TOP], 1u);
;             const unsigned tg = og / nx;
;             if (og + 1u == (tg + 1u) * nx) xb_add(&bar[XB_TOPGEN], 1u);
.LBB0_187:
	s_andn2_saveexec_b64 s[34:35], s[34:35]
	s_cbranch_execz .LBB0_207
	s_mov_b64 s[38:39], exec
	s_waitcnt lgkmcnt(0)
	s_waitcnt vmcnt(0)
	v_mbcnt_lo_u32_b32 v3, s38, 0
	v_mbcnt_hi_u32_b32 v3, s39, v3
	v_cmp_eq_u32_e32 vcc, 0, v3
	s_and_saveexec_b64 s[40:41], vcc
	s_cbranch_execz .LBB0_190
	s_bcnt1_i32_b64 s1, s[38:39]
	v_readlane_b32 s2, v253, 3
	v_mov_b32_e32 v4, s1
	v_readlane_b32 s3, v253, 4
	s_nop 4
	global_atomic_add v4, v175, v4, s[2:3] sc0

; __device__ __forceinline__ unsigned xb_add(unsigned* p, unsigned v) { return __hip_atomic_fetch_add(p, v, __ATOMIC_RELAXED, __HIP_MEMORY_SCOPE_AGENT); }
; __device__ __forceinline__ void xcd_barrier(const XcdBarrier& b) {
;     ...
;         if (old + 1u == (gen + 1u) * nloc) {
;             __builtin_amdgcn_fence(__ATOMIC_RELEASE, "agent");
;             asm volatile("s_waitcnt vmcnt(0)" ::: "memory");
;             const unsigned og = xb_add(&bar[XB_TOP], 1u);
;             const unsigned tg = og / nx;
;             if (og + 1u == (tg + 1u) * nx) xb_add(&bar[XB_TOPGEN], 1u);
.LBB0_278:
	s_andn2_saveexec_b64 s[2:3], s[34:35]
	s_cbranch_execz .LBB0_298
	s_mov_b64 s[34:35], exec
	s_waitcnt lgkmcnt(0)
	s_waitcnt vmcnt(0)
	v_mbcnt_lo_u32_b32 v3, s34, 0
	v_mbcnt_hi_u32_b32 v3, s35, v3
	v_cmp_eq_u32_e32 vcc, 0, v3
	s_and_saveexec_b64 s[38:39], vcc
	s_cbranch_execz .LBB0_281
	s_bcnt1_i32_b64 s1, s[34:35]
	v_readlane_b32 s2, v253, 3
	v_mov_b32_e32 v4, s1
	v_readlane_b32 s3, v253, 4
	s_nop 4
	global_atomic_add v4, v175, v4, s[2:3] sc0

; __device__ __forceinline__ unsigned xb_add(unsigned* p, unsigned v) { return __hip_atomic_fetch_add(p, v, __ATOMIC_RELAXED, __HIP_MEMORY_SCOPE_AGENT); }
; __device__ __forceinline__ void xcd_barrier(const XcdBarrier& b) {
;     ...
;         if (old + 1u == (gen + 1u) * nloc) {
;             __builtin_amdgcn_fence(__ATOMIC_RELEASE, "agent");
;             asm volatile("s_waitcnt vmcnt(0)" ::: "memory");
;             const unsigned og = xb_add(&bar[XB_TOP], 1u);
;             const unsigned tg = og / nx;
;             if (og + 1u == (tg + 1u) * nx) xb_add(&bar[XB_TOPGEN], 1u);
.LBB0_1840:
	s_mov_b64 s[34:35], exec
	s_waitcnt lgkmcnt(0)
	s_waitcnt vmcnt(0)
	v_mbcnt_lo_u32_b32 v3, s34, 0
	v_mbcnt_hi_u32_b32 v3, s35, v3
	v_cmp_eq_u32_e32 vcc, 0, v3
	s_and_saveexec_b64 s[38:39], vcc
	s_cbranch_execz .LBB0_1842
	s_bcnt1_i32_b64 s1, s[34:35]
	v_readlane_b32 s2, v253, 3
	v_mov_b32_e32 v4, s1
	v_readlane_b32 s3, v253, 4
	s_nop 4
	global_atomic_add v4, v175, v4, s[2:3] sc0
